# hg loops: IVT bf16 image built with v_perm_b32 instead of unpack + v_cvt_pk repack (bit-identical)
# baseline (speedup 1.0000x reference)
; #define LAS __attribute__((address_space(3)))
; __global__ void __launch_bounds__(NTHR, 2) fwd_megakernel(Prm P) {
;     extern __shared__ __attribute__((aligned(16))) unsigned char lds_raw[];
;     LAS unsigned char* lds = (LAS unsigned char*)lds_raw;
;     cg::grid_group grid = cg::this_grid();
;     const int wave = __builtin_amdgcn_readfirstlane(threadIdx.x >> 6);
;     if (P.coop == 2) grid.sync();
_Z14fwd_megakernel3Prm:
	s_mov_b32 s100, 0x5040100
	s_mov_b32 s101, 0x7060302
	s_mov_b32 s14, s2
	s_load_dwordx2 s[92:93], s[0:1], 0xc0
	s_load_dwordx4 s[8:11], s[0:1], 0xc8
	s_load_dword s2, s[0:1], 0xe0
	s_add_u32 s6, s0, 0xd8
	s_addc_u32 s7, s1, 0
	v_and_b32_e32 v1, 0x3ff, v0
	s_waitcnt lgkmcnt(0)
	s_mov_b64 s[4:5], s[8:9]
	v_writelane_b32 v255, s2, 0
	s_load_dwordx2 s[2:3], s[0:1], 0xd8
	s_cmp_lg_u32 s10, 2
	v_readfirstlane_b32 s16, v1
	s_waitcnt lgkmcnt(0)
	v_writelane_b32 v255, s2, 1
	s_nop 1
	v_writelane_b32 v255, s3, 2
	v_writelane_b32 v255, s4, 3
	s_movk_i32 s2, 0x3ff
	s_nop 0
	v_writelane_b32 v255, s5, 4
	v_writelane_b32 v255, s6, 5
	v_writelane_b32 v255, s7, 6
	s_cbranch_scc1 .LBB0_12
	v_lshrrev_b32_e32 v2, 20, v0
	v_lshrrev_b32_e32 v0, 10, v0
	v_or_b32_e32 v0, v0, v2
	v_and_or_b32 v0, v0, s2, v1
	v_cmp_eq_u32_e32 vcc, 0, v0
	s_barrier
	s_and_saveexec_b64 s[4:5], vcc
	s_cbranch_execz .LBB0_11
	buffer_wbl2 sc1
	s_load_dwordx2 s[6:7], s[6:7], 0x58
	s_mov_b64 s[8:9], exec
	v_mbcnt_lo_u32_b32 v0, s8, 0
	v_mbcnt_hi_u32_b32 v0, s9, v0
	v_cmp_eq_u32_e32 vcc, 0, v0
	s_waitcnt lgkmcnt(0)
	s_load_dword s2, s[6:7], 0x28
	s_and_saveexec_b64 s[10:11], vcc
	s_cbranch_execz .LBB0_4
	s_bcnt1_i32_b64 s3, s[8:9]
	v_mov_b32_e32 v1, 0
	v_mov_b32_e32 v2, s3
	global_atomic_add v1, v1, v2, s[6:7] offset:32 sc0

; #define LAS __attribute__((address_space(3)))
; __device__ __forceinline__ u32x4 pack8(const float (&f)[8]) { u32x4 w; w.x = pk2(f[0], f[1]); w.y = pk2(f[2], f[3]); w.z = pk2(f[4], f[5]); w.w = pk2(f[6], f[7]); return w; }
; template <bool FULL, bool STORE = true>
; __device__ __forceinline__ void hg_item(const Prm& P, LAS unsigned char* lds, int item, int wave) {
;     ...
;         for (int i = 0; i < 8; ++i) { f0[i] = __expf(c0[i]); f1[i] = __expf(c1[i]); ka[i] = 1.0f - f0[i]; kc[i] = 1.0f - f1[i]; t0 += c0[i]; t1 += c1[i]; }
;         *(LAS f32x2*)(lds + HL_TOT + (tg * 128 + k2) * 4) = (f32x2){t0, t1};
;         __syncthreads();
;         float off0 = 0.f, off1 = 0.f, bm0 = 0.f, bm1 = 0.f, bl0 = 0.f, bl1 = 0.f;
; #pragma unroll
;         for (int g8 = 0; g8 < 8; ++g8) { const f32x2 t2 = *(const LAS f32x2*)(lds + HL_TOT + (g8 * 128 + k2) * 4); if (g8 < tg) { off0 += t2.x; off1 += t2.y; } if (g8 < 4) { bm0 += t2.x; bm1 += t2.y; } bl0 += t2.x; bl1 += t2.y; }
;         {
;             float kd0[8], kd1[8], iv0[8], iv1[8];
;             float e0 = __expf(off0 + c0[0] - bm0), e1 = __expf(off1 + c1[0] - bm1);
;             const float ebm0 = __expf(bm0), ebm1 = __expf(bm1), ebl0 = __expf(bl0 - bm0), ebl1 = __expf(bl1 - bm1);
; #pragma unroll
;             for (int i = 0; i < 8; ++i) { if (i) { e0 *= f0[i]; e1 *= f1[i]; }
;                 const float r0 = __builtin_amdgcn_rcpf(e0), r1 = __builtin_amdgcn_rcpf(e1);
;                 kd0[i] = ka[i] * r0 * ebl0; kd1[i] = kc[i] * r1 * ebl1; iv0[i] = bflo(ivw[i]); iv1[i] = bfhi(ivw[i]);
;                 if (FULL) { const float qa = bflo(qw[i]), qc = bfhi(qw[i]); const int t = tg * 8 + i;
;                     *(LAS unsigned*)(lds + HL_QM + t * 272 + k2 * 2) = pk2(qa * e0, qc * e1);
;                     *(LAS unsigned*)(lds + HL_KM + t * 272 + k2 * 2) = pk2(ka[i] * r0, kc[i] * r1);
;                     *(LAS unsigned*)(lds + HL_QD + t * 272 + k2 * 2) = pk2(qa * e0 * ebm0, qc * e1 * ebm1); } }
;             *(LAS u32x4*)(lds + HL_KDT + k2 * 144 + tg * 16) = pack8(kd0); *(LAS u32x4*)(lds + HL_KDT + (k2 + 1) * 144 + tg * 16) = pack8(kd1);
;             *(LAS u32x4*)(lds + HL_IVT + k2 * 144 + tg * 16) = pack8(iv0); *(LAS u32x4*)(lds + HL_IVT + (k2 + 1) * 144 + tg * 16) = pack8(iv1);
;             if (tg == 0) { *(LAS f32x2*)(lds + HL_DC + k2 * 4) = (f32x2){__expf(bl0), __expf(bl1)}; sumlog0 += bl0; sumlog1 += bl1; }
.Lhgf_noload:
	v_mul_f32_e32 v33, 0x3fb8aa3b, v48
	v_exp_f32_e32 v93, v33
	v_mul_f32_e32 v33, 0x3fb8aa3b, v49
	v_exp_f32_e32 v95, v33
	v_mul_f32_e32 v33, 0x3fb8aa3b, v50
	v_exp_f32_e32 v96, v33
	v_mul_f32_e32 v33, 0x3fb8aa3b, v51
	v_exp_f32_e32 v98, v33
	v_mul_f32_e32 v33, 0x3fb8aa3b, v52
	v_exp_f32_e32 v97, v33
	v_mul_f32_e32 v33, 0x3fb8aa3b, v53
	v_pk_add_f32 v[62:63], v[46:47], 0 op_sel_hi:[1,0]
	v_exp_f32_e32 v99, v33
	v_mul_f32_e32 v33, 0x3fb8aa3b, v54
	v_exp_f32_e32 v100, v33
	v_mul_f32_e32 v33, 0x3fb8aa3b, v55
	v_pk_add_f32 v[62:63], v[62:63], v[48:49]
	v_exp_f32_e32 v102, v33
	v_mul_f32_e32 v33, 0x3fb8aa3b, v56
	v_pk_add_f32 v[62:63], v[62:63], v[50:51]
	v_exp_f32_e32 v101, v33
	v_mul_f32_e32 v33, 0x3fb8aa3b, v57
	v_pk_add_f32 v[62:63], v[62:63], v[52:53]
	v_exp_f32_e32 v103, v33
	v_mul_f32_e32 v33, 0x3fb8aa3b, v58
	v_pk_add_f32 v[62:63], v[62:63], v[54:55]
	v_exp_f32_e32 v104, v33
	v_mul_f32_e32 v33, 0x3fb8aa3b, v59
	v_pk_add_f32 v[62:63], v[62:63], v[56:57]
	v_exp_f32_e32 v106, v33
	v_mul_f32_e32 v33, 0x3fb8aa3b, v60
	v_pk_add_f32 v[62:63], v[62:63], v[58:59]
	v_exp_f32_e32 v105, v33
	v_pk_add_f32 v[62:63], v[62:63], v[60:61]
	v_add_u32_e32 v33, s45, v64
	ds_write_b64 v33, v[62:63]
	v_add_u32_e32 v33, 0, v64
	v_add_u32_e32 v62, 0x20800, v33
	s_waitcnt lgkmcnt(0)
	s_barrier
	ds_read2st64_b64 v[76:79], v62 offset1:1
	v_mul_f32_e32 v80, 0x3fb8aa3b, v61
	v_exp_f32_e32 v107, v80
	ds_read2st64_b64 v[80:83], v62 offset0:2 offset1:3
	ds_read2st64_b64 v[84:87], v62 offset0:4 offset1:5
	ds_read2st64_b64 v[88:91], v62 offset0:6 offset1:7
	s_waitcnt lgkmcnt(3)
	v_pk_add_f32 v[62:63], v[76:77], 0 op_sel_hi:[1,0]
	v_cndmask_b32_e64 v77, v62, 0, s[88:89]
	v_cndmask_b32_e64 v76, v63, 0, s[88:89]
	v_add_f32_e32 v92, v78, v77
	v_add_f32_e32 v94, v79, v76
	v_cndmask_b32_e64 v77, v77, v92, s[4:5]
	v_cndmask_b32_e64 v76, v76, v94, s[4:5]
	v_pk_add_f32 v[62:63], v[62:63], v[78:79]
	s_waitcnt lgkmcnt(2)
	v_add_f32_e32 v78, v80, v77
	v_add_f32_e32 v79, v81, v76
	v_cndmask_b32_e64 v77, v77, v78, s[6:7]
	v_cndmask_b32_e64 v76, v76, v79, s[6:7]
	v_add_f32_e32 v78, v82, v77
	v_pk_add_f32 v[62:63], v[62:63], v[80:81]
	v_add_f32_e32 v79, v83, v76
	v_cndmask_b32_e64 v78, v77, v78, s[8:9]
	v_cndmask_b32_e64 v79, v76, v79, s[8:9]
	v_pk_add_f32 v[76:77], v[62:63], v[82:83]
	s_waitcnt lgkmcnt(1)
	v_add_f32_e32 v62, v84, v78
	v_cndmask_b32_e64 v78, v78, v62, s[10:11]
	v_add_f32_e32 v80, v86, v78
	v_add_f32_e32 v63, v85, v79
	v_cndmask_b32_e64 v78, v78, v80, s[12:13]
	v_cndmask_b32_e64 v79, v79, v63, s[10:11]
	s_waitcnt lgkmcnt(0)
	v_add_f32_e32 v80, v88, v78
	v_add_f32_e32 v81, v87, v79
	v_cndmask_b32_e64 v78, v78, v80, s[14:15]
	v_cndmask_b32_e64 v79, v79, v81, s[12:13]
	v_add_f32_e32 v80, v90, v78
	v_add_f32_e32 v81, v89, v79
	v_cndmask_b32_e64 v78, v78, v80, s[16:17]
	v_pk_add_f32 v[62:63], v[76:77], v[84:85]
	v_cndmask_b32_e64 v79, v79, v81, s[14:15]
	v_add_f32_e32 v78, v46, v78
	v_pk_add_f32 v[62:63], v[62:63], v[86:87]
	v_add_f32_e32 v81, v91, v79
	v_sub_f32_e32 v78, v78, v76
	v_pk_add_f32 v[62:63], v[62:63], v[88:89]
	v_cndmask_b32_e64 v79, v79, v81, s[16:17]
	v_mul_f32_e32 v78, 0x3fb8aa3b, v78
	v_pk_add_f32 v[62:63], v[62:63], v[90:91]
	v_exp_f32_e32 v81, v78
	v_add_f32_e32 v78, v47, v79
	v_sub_f32_e32 v78, v78, v77
	v_pk_add_f32 v[76:77], v[62:63], v[76:77] neg_lo:[0,1] neg_hi:[0,1]
	v_mul_f32_e32 v78, 0x3fb8aa3b, v78
	v_mul_f32_e32 v77, 0x3fb8aa3b, v77
	v_exp_f32_e32 v79, v78
	v_exp_f32_e32 v78, v77
	v_mul_f32_e32 v77, 0x3fb8aa3b, v47
	v_exp_f32_e32 v94, v77
	v_mul_f32_e32 v77, 0x3fb8aa3b, v46
	v_exp_f32_e32 v92, v77
	v_mul_f32_e32 v77, v93, v81
	v_mul_f32_e32 v76, 0x3fb8aa3b, v76
	v_rcp_f32_e32 v80, v81
	v_rcp_f32_e32 v81, v77
	v_exp_f32_e32 v76, v76
	v_rcp_f32_e32 v82, v79
	v_mul_f32_e32 v79, v95, v79
	v_rcp_f32_e32 v83, v79
	v_pk_add_f32 v[84:85], v[92:93], 1.0 op_sel_hi:[1,0] neg_lo:[1,0] neg_hi:[1,0]
	v_pk_add_f32 v[88:89], v[96:97], 1.0 op_sel_hi:[1,0] neg_lo:[1,0] neg_hi:[1,0]
	v_pk_mul_f32 v[80:81], v[84:85], v[80:81]
	v_pk_add_f32 v[84:85], v[94:95], 1.0 op_sel_hi:[1,0] neg_lo:[1,0] neg_hi:[1,0]
	v_pk_mul_f32 v[80:81], v[76:77], v[80:81] op_sel_hi:[0,1]
	v_mul_f32_e32 v77, v96, v77
	v_pk_mul_f32 v[82:83], v[84:85], v[82:83]
	v_rcp_f32_e32 v84, v77
	v_mul_f32_e32 v77, v97, v77
	v_pk_mul_f32 v[82:83], v[78:79], v[82:83] op_sel_hi:[0,1]
	v_mul_f32_e32 v79, v98, v79
	v_rcp_f32_e32 v85, v77
	v_rcp_f32_e32 v86, v79
	v_mul_f32_e32 v79, v99, v79
	v_rcp_f32_e32 v87, v79
	v_pk_mul_f32 v[84:85], v[88:89], v[84:85]
	v_pk_add_f32 v[88:89], v[98:99], 1.0 op_sel_hi:[1,0] neg_lo:[1,0] neg_hi:[1,0]
	v_pk_mul_f32 v[84:85], v[76:77], v[84:85] op_sel_hi:[0,1]
	v_mul_f32_e32 v77, v100, v77
	v_pk_mul_f32 v[86:87], v[88:89], v[86:87]
	v_rcp_f32_e32 v88, v77
	v_mul_f32_e32 v77, v101, v77
	v_pk_mul_f32 v[86:87], v[78:79], v[86:87] op_sel_hi:[0,1]
	v_mul_f32_e32 v79, v102, v79
	v_rcp_f32_e32 v89, v77
	v_rcp_f32_e32 v90, v79
	v_mul_f32_e32 v79, v103, v79
	v_rcp_f32_e32 v91, v79
	v_pk_add_f32 v[92:93], v[100:101], 1.0 op_sel_hi:[1,0] neg_lo:[1,0] neg_hi:[1,0]
	v_pk_add_f32 v[96:97], v[104:105], 1.0 op_sel_hi:[1,0] neg_lo:[1,0] neg_hi:[1,0]
	v_pk_mul_f32 v[88:89], v[92:93], v[88:89]
	v_pk_add_f32 v[92:93], v[102:103], 1.0 op_sel_hi:[1,0] neg_lo:[1,0] neg_hi:[1,0]
	v_pk_mul_f32 v[88:89], v[76:77], v[88:89] op_sel_hi:[0,1]
	v_mul_f32_e32 v77, v104, v77
	v_pk_mul_f32 v[90:91], v[92:93], v[90:91]
	v_rcp_f32_e32 v92, v77
	v_mul_f32_e32 v77, v105, v77
	v_pk_mul_f32 v[90:91], v[78:79], v[90:91] op_sel_hi:[0,1]
	v_mul_f32_e32 v79, v106, v79
	v_rcp_f32_e32 v93, v77
	v_mul_f32_e32 v77, v107, v79
	v_rcp_f32_e32 v94, v79
	v_rcp_f32_e32 v95, v77
	v_pk_mul_f32 v[92:93], v[96:97], v[92:93]
	v_pk_mul_f32 v[92:93], v[76:77], v[92:93] op_sel_hi:[0,1]
	v_pk_add_f32 v[76:77], v[106:107], 1.0 op_sel_hi:[1,0] neg_lo:[1,0] neg_hi:[1,0]
	v_pk_mul_f32 v[76:77], v[76:77], v[94:95]
	v_pk_mul_f32 v[94:95], v[78:79], v[76:77] op_sel_hi:[0,1]
	v_cvt_pk_bf16_f32 v76, v80, v81
	v_cvt_pk_bf16_f32 v77, v84, v85
	v_cvt_pk_bf16_f32 v78, v88, v89
	v_cvt_pk_bf16_f32 v79, v92, v93
	v_add_u32_e32 v80, s46, v66
	ds_write_b128 v80, v[76:79] offset:52224
	v_cvt_pk_bf16_f32 v76, v82, v83
	v_cvt_pk_bf16_f32 v77, v86, v87
	v_cvt_pk_bf16_f32 v78, v90, v91
	v_cvt_pk_bf16_f32 v79, v94, v95
	ds_write_b128 v80, v[76:79] offset:52368
	v_perm_b32 v76, v65, v37, s100
	v_perm_b32 v77, v69, v68, s100
	v_perm_b32 v78, v71, v70, s100
	v_perm_b32 v79, v75, v72, s100
	v_add_u32_e32 v80, s47, v66
	ds_write_b128 v80, v[76:79]
	v_perm_b32 v76, v65, v37, s101
	v_perm_b32 v77, v69, v68, s101
	v_perm_b32 v78, v71, v70, s101
	v_perm_b32 v79, v75, v72, s101
	s_and_b64 vcc, exec, s[0:1]
	ds_write_b128 v80, v[76:79] offset:144
	s_cbranch_vccnz .LBB0_704
	v_mul_f32_e32 v76, 0x3fb8aa3b, v62
	v_mul_f32_e32 v77, 0x3fb8aa3b, v63
	v_exp_f32_e32 v76, v76
	v_exp_f32_e32 v77, v77
	v_pk_add_f32 v[40:41], v[40:41], v[62:63]
	v_add_u32_e32 v33, 0x21800, v33
	ds_write_b64 v33, v[76:77]

; #define LAS __attribute__((address_space(3)))
; __device__ __forceinline__ unsigned pk2(float lo, float hi) { typedef float f2v __attribute__((ext_vector_type(2))); typedef __bf16 b2v __attribute__((ext_vector_type(2))); const f2v v = {lo, hi}; const b2v b = __builtin_convertvector(v, b2v); return __builtin_bit_cast(unsigned, b); }
; template <bool FULL, bool STORE = true>
; __device__ __forceinline__ void hg_item(const Prm& P, LAS unsigned char* lds, int item, int wave) {
;     ...
;         float off0 = 0.f, off1 = 0.f, bm0 = 0.f, bm1 = 0.f, bl0 = 0.f, bl1 = 0.f;
; #pragma unroll
;         for (int g8 = 0; g8 < 8; ++g8) { const f32x2 t2 = *(const LAS f32x2*)(lds + HL_TOT + (g8 * 128 + k2) * 4); if (g8 < tg) { off0 += t2.x; off1 += t2.y; } if (g8 < 4) { bm0 += t2.x; bm1 += t2.y; } bl0 += t2.x; bl1 += t2.y; }
;         {
;             float kd0[8], kd1[8], iv0[8], iv1[8];
;             float e0 = __expf(off0 + c0[0] - bm0), e1 = __expf(off1 + c1[0] - bm1);
;             const float ebm0 = __expf(bm0), ebm1 = __expf(bm1), ebl0 = __expf(bl0 - bm0), ebl1 = __expf(bl1 - bm1);
; #pragma unroll
;             for (int i = 0; i < 8; ++i) { if (i) { e0 *= f0[i]; e1 *= f1[i]; }
;                 const float r0 = __builtin_amdgcn_rcpf(e0), r1 = __builtin_amdgcn_rcpf(e1);
;                 kd0[i] = ka[i] * r0 * ebl0; kd1[i] = kc[i] * r1 * ebl1; iv0[i] = bflo(ivw[i]); iv1[i] = bfhi(ivw[i]);
;                 if (FULL) { const float qa = bflo(qw[i]), qc = bfhi(qw[i]); const int t = tg * 8 + i;
;                     *(LAS unsigned*)(lds + HL_QM + t * 272 + k2 * 2) = pk2(qa * e0, qc * e1);
;                     *(LAS unsigned*)(lds + HL_KM + t * 272 + k2 * 2) = pk2(ka[i] * r0, kc[i] * r1);
;                     *(LAS unsigned*)(lds + HL_QD + t * 272 + k2 * 2) = pk2(qa * e0 * ebm0, qc * e1 * ebm1); } }
.LBB0_840:
	s_nop 0
	v_add_u32_e32 v44, 0, v126
	v_add_u32_e32 v64, 0x20800, v44
	v_mul_f32_e32 v45, 0x3fb8aa3b, v92
	v_mul_f32_e32 v34, 0x3fb8aa3b, v80
	v_exp_f32_e32 v46, v34
	v_mul_f32_e32 v34, 0x3fb8aa3b, v81
	ds_read2st64_b64 v[36:39], v64 offset1:1
	ds_read2st64_b64 v[56:59], v64 offset0:2 offset1:3
	v_exp_f32_e32 v32, v45
	v_exp_f32_e32 v47, v34
	v_mul_f32_e32 v34, 0x3fb8aa3b, v82
	s_waitcnt lgkmcnt(1)
	v_add_f32_e32 v36, 0, v36
	v_cndmask_b32_e64 v60, v36, 0, s[88:89]
	v_add_f32_e32 v37, 0, v37
	v_add_f32_e32 v61, v38, v60
	v_cndmask_b32_e64 v45, v37, 0, s[88:89]
	v_cndmask_b32_e64 v60, v60, v61, s[6:7]
	v_add_f32_e32 v62, v39, v45
	v_add_f32_e32 v36, v36, v38
	v_add_f32_e32 v38, v37, v39
	s_waitcnt lgkmcnt(0)
	v_add_f32_e32 v37, v56, v60
	v_cndmask_b32_e64 v45, v45, v62, s[6:7]
	v_cndmask_b32_e64 v65, v60, v37, s[8:9]
	ds_read2st64_b64 v[60:63], v64 offset0:4 offset1:5
	v_add_f32_e32 v39, v57, v45
	v_cndmask_b32_e64 v45, v45, v39, s[8:9]
	v_add_f32_e32 v37, v36, v56
	v_add_f32_e32 v39, v38, v57
	v_add_f32_e32 v36, v58, v65
	v_add_f32_e32 v38, v59, v45
	v_cndmask_b32_e64 v38, v45, v38, s[4:5]
	v_cndmask_b32_e64 v36, v65, v36, s[4:5]
	ds_read2st64_b64 v[64:67], v64 offset0:6 offset1:7
	s_waitcnt lgkmcnt(1)
	v_add_f32_e32 v45, v60, v36
	v_add_f32_e32 v56, v61, v38
	v_cndmask_b32_e64 v38, v38, v56, s[10:11]
	v_cndmask_b32_e64 v36, v36, v45, s[10:11]
	v_add_f32_e32 v45, v62, v36
	v_add_f32_e32 v56, v63, v38
	v_cndmask_b32_e64 v38, v38, v56, s[12:13]
	v_cndmask_b32_e64 v36, v36, v45, s[12:13]
	s_waitcnt lgkmcnt(0)
	v_add_f32_e32 v45, v64, v36
	v_add_f32_e32 v56, v65, v38
	v_cndmask_b32_e64 v38, v38, v56, s[14:15]
	v_cndmask_b32_e64 v36, v36, v45, s[14:15]
	v_add_f32_e32 v45, v66, v36
	v_add_f32_e32 v56, v67, v38
	v_cndmask_b32_e64 v38, v38, v56, s[16:17]
	v_cndmask_b32_e64 v36, v36, v45, s[16:17]
	v_mov_b32_e32 v56, v78
	v_mov_b32_e32 v57, v58
	v_pk_add_f32 v[56:57], v[56:57], v[36:37]
	v_mov_b32_e32 v58, v79
	v_pk_add_f32 v[36:37], v[56:57], v[60:61] op_sel:[1,0] op_sel_hi:[0,1]
	v_pk_add_f32 v[36:37], v[36:37], v[62:63]
	v_pk_add_f32 v[58:59], v[58:59], v[38:39]
	v_pk_add_f32 v[36:37], v[36:37], v[64:65]
	v_pk_add_f32 v[38:39], v[58:59], v[60:61]
	v_pk_add_f32 v[36:37], v[36:37], v[66:67]
	v_pk_add_f32 v[38:39], v[38:39], v[62:63]
	v_sub_f32_e32 v37, v56, v57
	v_mul_f32_e32 v37, 0x3fb8aa3b, v37
	v_exp_f32_e32 v72, v37
	v_sub_f32_e32 v37, v58, v59
	v_mul_f32_e32 v37, 0x3fb8aa3b, v37
	v_exp_f32_e32 v73, v37
	v_mul_f32_e32 v37, 0x3fb8aa3b, v57
	v_exp_f32_e32 v60, v37
	v_mul_f32_e32 v37, 0x3fb8aa3b, v59
	v_mul_f32_e32 v45, 0x3fb8aa3b, v79
	v_pk_add_f32 v[38:39], v[38:39], v[64:65]
	v_exp_f32_e32 v61, v37
	v_sub_f32_e32 v37, v36, v57
	v_exp_f32_e32 v57, v45
	v_mul_f32_e32 v45, 0x3fb8aa3b, v78
	v_pk_add_f32 v[38:39], v[38:39], v[66:67]
	v_mul_f32_e32 v37, 0x3fb8aa3b, v37
	v_exp_f32_e32 v56, v45
	v_exp_f32_e32 v38, v37
	v_sub_f32_e32 v37, v39, v59
	v_rcp_f32_e32 v58, v72
	v_rcp_f32_e32 v59, v73
	v_pk_add_f32 v[56:57], v[56:57], 1.0 op_sel_hi:[1,0] neg_lo:[1,0] neg_hi:[1,0]
	v_mul_f32_e32 v37, 0x3fb8aa3b, v37
	v_exp_f32_e32 v62, v37
	v_pk_mul_f32 v[56:57], v[56:57], v[58:59]
	v_lshlrev_b32_e32 v58, 16, v111
	v_and_b32_e32 v59, 0xffff0000, v111
	v_pk_mul_f32 v[58:59], v[72:73], v[58:59]
	v_lshlrev_b32_e32 v66, 16, v113
	v_cvt_pk_bf16_f32 v63, v58, v59
	v_pk_mul_f32 v[58:59], v[60:61], v[58:59]
	v_and_b32_e32 v67, 0xffff0000, v113
	v_cvt_pk_bf16_f32 v102, v58, v59
	v_pk_mul_f32 v[58:59], v[46:47], v[72:73]
	v_pk_add_f32 v[46:47], v[46:47], 1.0 op_sel_hi:[1,0] neg_lo:[1,0] neg_hi:[1,0]
	v_rcp_f32_e32 v64, v58
	v_rcp_f32_e32 v65, v59
	v_exp_f32_e32 v68, v34
	v_mul_f32_e32 v34, 0x3fb8aa3b, v83
	v_pk_mul_f32 v[66:67], v[58:59], v[66:67]
	v_pk_mul_f32 v[46:47], v[46:47], v[64:65]
	v_exp_f32_e32 v69, v34
	v_mul_f32_e32 v34, 0x3fb8aa3b, v84
	v_cvt_pk_bf16_f32 v74, v56, v57
	v_mov_b32_e32 v64, v56
	v_mov_b32_e32 v56, v57
	v_mov_b32_e32 v57, v47
	v_cvt_pk_bf16_f32 v72, v66, v67
	v_exp_f32_e32 v70, v34
	v_mul_f32_e32 v34, 0x3fb8aa3b, v85
	v_mov_b32_e32 v65, v46
	v_pk_mul_f32 v[56:57], v[62:63], v[56:57] op_sel_hi:[0,1]
	ds_write2_b32 v132, v63, v72 offset1:68
	v_cvt_pk_bf16_f32 v46, v46, v47
	v_add_u32_e32 v63, 0x4400, v132
	v_exp_f32_e32 v71, v34
	ds_write2_b32 v63, v74, v46 offset1:68
	v_pk_mul_f32 v[46:47], v[60:61], v[66:67]
	v_add_u32_e32 v72, 0x8800, v132
	v_cvt_pk_bf16_f32 v46, v46, v47
	ds_write2_b32 v72, v102, v46 offset1:68
	v_pk_mul_f32 v[46:47], v[68:69], v[58:59]
	v_lshlrev_b32_e32 v66, 16, v115
	v_and_b32_e32 v67, 0xffff0000, v115
	v_pk_mul_f32 v[66:67], v[46:47], v[66:67]
	v_rcp_f32_e32 v58, v46
	v_rcp_f32_e32 v59, v47
	v_cvt_pk_bf16_f32 v102, v66, v67
	v_pk_mul_f32 v[66:67], v[60:61], v[66:67]
	v_pk_mul_f32 v[46:47], v[70:71], v[46:47]
	v_mul_f32_e32 v34, 0x3fb8aa3b, v86
	v_cvt_pk_bf16_f32 v106, v66, v67
	v_rcp_f32_e32 v66, v46
	v_rcp_f32_e32 v67, v47
	v_exp_f32_e32 v42, v34
	v_mul_f32_e32 v34, 0x3fb8aa3b, v87
	v_exp_f32_e32 v43, v34
	v_pk_add_f32 v[68:69], v[68:69], 1.0 op_sel_hi:[1,0] neg_lo:[1,0] neg_hi:[1,0]
; #define LAS __attribute__((address_space(3)))
; __device__ __forceinline__ unsigned pk2(float lo, float hi) { typedef float f2v __attribute__((ext_vector_type(2))); typedef __bf16 b2v __attribute__((ext_vector_type(2))); const f2v v = {lo, hi}; const b2v b = __builtin_convertvector(v, b2v); return __builtin_bit_cast(unsigned, b); }
; __device__ __forceinline__ u32x4 pack8(const float (&f)[8]) { u32x4 w; w.x = pk2(f[0], f[1]); w.y = pk2(f[2], f[3]); w.z = pk2(f[4], f[5]); w.w = pk2(f[6], f[7]); return w; }
; template <bool FULL, bool STORE = true>
; __device__ __forceinline__ void hg_item(const Prm& P, LAS unsigned char* lds, int item, int wave) {
;     ...
;             for (int i = 0; i < 8; ++i) { if (i) { e0 *= f0[i]; e1 *= f1[i]; }
;                 const float r0 = __builtin_amdgcn_rcpf(e0), r1 = __builtin_amdgcn_rcpf(e1);
;                 kd0[i] = ka[i] * r0 * ebl0; kd1[i] = kc[i] * r1 * ebl1; iv0[i] = bflo(ivw[i]); iv1[i] = bfhi(ivw[i]);
;                 if (FULL) { const float qa = bflo(qw[i]), qc = bfhi(qw[i]); const int t = tg * 8 + i;
;                     *(LAS unsigned*)(lds + HL_QM + t * 272 + k2 * 2) = pk2(qa * e0, qc * e1);
;                     *(LAS unsigned*)(lds + HL_KM + t * 272 + k2 * 2) = pk2(ka[i] * r0, kc[i] * r1);
;                     *(LAS unsigned*)(lds + HL_QD + t * 272 + k2 * 2) = pk2(qa * e0 * ebm0, qc * e1 * ebm1); } }
;             *(LAS u32x4*)(lds + HL_KDT + k2 * 144 + tg * 16) = pack8(kd0); *(LAS u32x4*)(lds + HL_KDT + (k2 + 1) * 144 + tg * 16) = pack8(kd1);
;             *(LAS u32x4*)(lds + HL_IVT + k2 * 144 + tg * 16) = pack8(iv0); *(LAS u32x4*)(lds + HL_IVT + (k2 + 1) * 144 + tg * 16) = pack8(iv1);
;             if (tg == 0) { *(LAS f32x2*)(lds + HL_DC + k2 * 4) = (f32x2){__expf(bl0), __expf(bl1)}; sumlog0 += bl0; sumlog1 += bl1; }
	v_pk_add_f32 v[70:71], v[70:71], 1.0 op_sel_hi:[1,0] neg_lo:[1,0] neg_hi:[1,0]
	v_pk_mul_f32 v[58:59], v[68:69], v[58:59]
	v_lshlrev_b32_e32 v68, 16, v117
	v_and_b32_e32 v69, 0xffff0000, v117
	v_pk_mul_f32 v[66:67], v[70:71], v[66:67]
	v_cvt_pk_bf16_f32 v105, v58, v59
	v_mov_b32_e32 v71, v66
	v_pk_mul_f32 v[68:69], v[46:47], v[68:69]
	v_cvt_pk_bf16_f32 v66, v66, v67
	v_mul_f32_e32 v34, 0x3fb8aa3b, v88
	v_mov_b32_e32 v70, v58
	v_mov_b32_e32 v58, v59
	v_mov_b32_e32 v59, v67
	ds_write2_b32 v63, v105, v66 offset0:136 offset1:204
	v_pk_mul_f32 v[66:67], v[60:61], v[68:69]
	v_pk_mul_f32 v[46:47], v[42:43], v[46:47]
	v_exp_f32_e32 v40, v34
	v_mul_f32_e32 v34, 0x3fb8aa3b, v89
	v_pk_mul_f32 v[58:59], v[62:63], v[58:59] op_sel_hi:[0,1]
	v_cvt_pk_bf16_f32 v63, v66, v67
	v_rcp_f32_e32 v66, v46
	v_rcp_f32_e32 v67, v47
	v_exp_f32_e32 v41, v34
	v_cvt_pk_bf16_f32 v161, v68, v69
	v_lshlrev_b32_e32 v68, 16, v119
	v_and_b32_e32 v69, 0xffff0000, v119
	v_pk_add_f32 v[42:43], v[42:43], 1.0 op_sel_hi:[1,0] neg_lo:[1,0] neg_hi:[1,0]
	ds_write2_b32 v72, v106, v63 offset0:136 offset1:204
	v_pk_mul_f32 v[42:43], v[42:43], v[66:67]
	v_pk_mul_f32 v[66:67], v[46:47], v[68:69]
	v_pk_mul_f32 v[46:47], v[40:41], v[46:47]
	v_cvt_pk_bf16_f32 v63, v66, v67
	v_pk_mul_f32 v[66:67], v[60:61], v[66:67]
	v_lshlrev_b32_e32 v68, 16, v121
	v_cvt_pk_bf16_f32 v106, v66, v67
	v_rcp_f32_e32 v66, v46
	v_rcp_f32_e32 v67, v47
	v_and_b32_e32 v69, 0xffff0000, v121
	v_mul_f32_e32 v34, 0x3fb8aa3b, v90
	v_mul_f32_e32 v35, 0x3fb8aa3b, v91
	v_pk_add_f32 v[40:41], v[40:41], 1.0 op_sel_hi:[1,0] neg_lo:[1,0] neg_hi:[1,0]
	v_pk_mul_f32 v[68:69], v[46:47], v[68:69]
	v_exp_f32_e32 v34, v34
	v_exp_f32_e32 v35, v35
	v_pk_mul_f32 v[40:41], v[40:41], v[66:67]
	v_cvt_pk_bf16_f32 v163, v68, v69
	v_add_u32_e32 v164, 0x400, v132
	v_cvt_pk_bf16_f32 v105, v42, v43
	v_mov_b32_e32 v67, v40
	ds_write2_b32 v164, v63, v163 offset0:16 offset1:84
	v_cvt_pk_bf16_f32 v40, v40, v41
	v_add_u32_e32 v163, 0x4800, v132
	v_mov_b32_e32 v66, v42
	v_mov_b32_e32 v42, v43
	v_mov_b32_e32 v43, v41
	ds_write2_b32 v163, v105, v40 offset0:16 offset1:84
	v_pk_mul_f32 v[40:41], v[60:61], v[68:69]
	v_add_u32_e32 v105, 0x8c00, v132
	v_cvt_pk_bf16_f32 v40, v40, v41
	ds_write2_b32 v105, v106, v40 offset0:16 offset1:84
	v_pk_mul_f32 v[40:41], v[34:35], v[46:47]
	v_mul_f32_e32 v33, 0x3fb8aa3b, v93
	v_rcp_f32_e32 v46, v40
	v_rcp_f32_e32 v47, v41
	v_exp_f32_e32 v33, v33
	v_lshlrev_b32_e32 v68, 16, v123
	v_and_b32_e32 v69, 0xffff0000, v123
	v_pk_add_f32 v[34:35], v[34:35], 1.0 op_sel_hi:[1,0] neg_lo:[1,0] neg_hi:[1,0]
	v_pk_mul_f32 v[42:43], v[62:63], v[42:43] op_sel_hi:[0,1]
	v_pk_mul_f32 v[34:35], v[34:35], v[46:47]
	v_pk_mul_f32 v[46:47], v[40:41], v[68:69]
	v_pk_mul_f32 v[40:41], v[32:33], v[40:41]
	v_cvt_pk_bf16_f32 v166, v46, v47
	v_pk_mul_f32 v[46:47], v[60:61], v[46:47]
	v_pk_add_f32 v[32:33], v[32:33], 1.0 op_sel_hi:[1,0] neg_lo:[1,0] neg_hi:[1,0]
	v_cvt_pk_bf16_f32 v168, v46, v47
	v_rcp_f32_e32 v46, v40
	v_rcp_f32_e32 v47, v41
	v_cvt_pk_bf16_f32 v167, v34, v35
	s_waitcnt vmcnt(2)
	v_lshlrev_b32_e32 v68, 16, v125
	v_and_b32_e32 v69, 0xffff0000, v125
	v_pk_mul_f32 v[32:33], v[32:33], v[46:47]
	v_mov_b32_e32 v46, v34
	v_mov_b32_e32 v34, v35
	v_mov_b32_e32 v35, v33
	v_mov_b32_e32 v47, v32
	v_pk_mul_f32 v[62:63], v[62:63], v[34:35] op_sel_hi:[0,1]
	v_pk_mul_f32 v[34:35], v[40:41], v[68:69]
	v_cvt_pk_bf16_f32 v32, v32, v33
	ds_write2_b32 v163, v167, v32 offset0:152 offset1:220
	v_pk_mul_f32 v[32:33], v[60:61], v[34:35]
	v_pk_mul_f32 v[64:65], v[38:39], v[64:65] op_sel_hi:[0,1]
	v_pk_mul_f32 v[70:71], v[38:39], v[70:71] op_sel_hi:[0,1]
	v_pk_mul_f32 v[66:67], v[38:39], v[66:67] op_sel_hi:[0,1]
	v_pk_mul_f32 v[46:47], v[38:39], v[46:47] op_sel_hi:[0,1]
	v_cvt_pk_bf16_f32 v38, v34, v35
	v_cvt_pk_bf16_f32 v32, v32, v33
	ds_write2_b32 v164, v166, v38 offset0:152 offset1:220
	ds_write2_b32 v105, v168, v32 offset0:152 offset1:220
	v_cvt_pk_bf16_f32 v32, v64, v65
	v_cvt_pk_bf16_f32 v33, v70, v71
	v_cvt_pk_bf16_f32 v34, v66, v67
	v_cvt_pk_bf16_f32 v35, v46, v47
	v_add_u32_e32 v38, s61, v127
	ds_write2_b32 v132, v102, v161 offset0:136 offset1:204
	ds_write_b128 v38, v[32:35] offset:52224
	v_cvt_pk_bf16_f32 v32, v56, v57
	v_cvt_pk_bf16_f32 v33, v58, v59
	v_cvt_pk_bf16_f32 v34, v42, v43
	v_cvt_pk_bf16_f32 v35, v62, v63
	ds_write_b128 v38, v[32:35] offset:52368
	v_perm_b32 v32, v112, v110, s100
	v_perm_b32 v33, v116, v114, s100
	v_perm_b32 v34, v120, v118, s100
	v_perm_b32 v35, v124, v122, s100
	v_add_u32_e32 v37, s58, v127
	ds_write_b128 v37, v[32:35]
	v_perm_b32 v32, v112, v110, s101
	v_perm_b32 v33, v116, v114, s101
	v_perm_b32 v34, v120, v118, s101
	v_perm_b32 v35, v124, v122, s101
	s_and_b64 vcc, exec, s[0:1]
	ds_write_b128 v37, v[32:35] offset:144
	s_cbranch_vccnz .LBB0_842
	v_mul_f32_e32 v32, 0x3fb8aa3b, v36
	v_mul_f32_e32 v33, 0x3fb8aa3b, v39
	v_exp_f32_e32 v32, v32
	v_exp_f32_e32 v33, v33
	v_add_u32_e32 v34, 0x21800, v44
	ds_write_b64 v34, v[32:33]

; __global__ void __launch_bounds__(NTHR, 2) fwd_megakernel(Prm P) {
	.amdhsa_kernel _Z14fwd_megakernel3Prm
		.amdhsa_group_segment_fixed_size 0
		.amdhsa_private_segment_fixed_size 0
		.amdhsa_kernarg_size 472
		.amdhsa_user_sgpr_count 2
		.amdhsa_user_sgpr_dispatch_ptr 0
		.amdhsa_user_sgpr_queue_ptr 0
		.amdhsa_user_sgpr_kernarg_segment_ptr 1
		.amdhsa_user_sgpr_dispatch_id 0
		.amdhsa_user_sgpr_kernarg_preload_length 0
		.amdhsa_user_sgpr_kernarg_preload_offset 0
		.amdhsa_user_sgpr_private_segment_size 0
		.amdhsa_uses_dynamic_stack 0
		.amdhsa_enable_private_segment 0
		.amdhsa_system_sgpr_workgroup_id_x 1
		.amdhsa_system_sgpr_workgroup_id_y 0
		.amdhsa_system_sgpr_workgroup_id_z 0
		.amdhsa_system_sgpr_workgroup_info 0
		.amdhsa_system_vgpr_workitem_id 2
		.amdhsa_next_free_vgpr 256
		.amdhsa_next_free_sgpr 102
		.amdhsa_accum_offset 256
		.amdhsa_reserve_vcc 1
		.amdhsa_float_round_mode_32 0
		.amdhsa_float_round_mode_16_64 0
		.amdhsa_float_denorm_mode_32 3
		.amdhsa_float_denorm_mode_16_64 3
		.amdhsa_dx10_clamp 1
		.amdhsa_ieee_mode 1
		.amdhsa_fp16_overflow 0
		.amdhsa_tg_split 0
		.amdhsa_exception_fp_ieee_invalid_op 0
		.amdhsa_exception_fp_denorm_src 0
		.amdhsa_exception_fp_ieee_div_zero 0
		.amdhsa_exception_fp_ieee_overflow 0
		.amdhsa_exception_fp_ieee_underflow 0
		.amdhsa_exception_fp_ieee_inexact 0
		.amdhsa_exception_int_div_zero 0
	.end_amdhsa_kernel

; __global__ void __launch_bounds__(NTHR, 2) fwd_megakernel(Prm P) {
amdhsa.kernels:
  - .agpr_count:     0
    .args:
      - .offset:         0
        .size:           216
        .value_kind:     by_value
      - .offset:         216
        .size:           4
        .value_kind:     hidden_block_count_x
      - .offset:         220
        .size:           4
        .value_kind:     hidden_block_count_y
      - .offset:         224
        .size:           4
        .value_kind:     hidden_block_count_z
      - .offset:         228
        .size:           2
        .value_kind:     hidden_group_size_x
      - .offset:         230
        .size:           2
        .value_kind:     hidden_group_size_y
      - .offset:         232
        .size:           2
        .value_kind:     hidden_group_size_z
      - .offset:         234
        .size:           2
        .value_kind:     hidden_remainder_x
      - .offset:         236
        .size:           2
        .value_kind:     hidden_remainder_y
      - .offset:         238
        .size:           2
        .value_kind:     hidden_remainder_z
      - .offset:         256
        .size:           8
        .value_kind:     hidden_global_offset_x
      - .offset:         264
        .size:           8
        .value_kind:     hidden_global_offset_y
      - .offset:         272
        .size:           8
        .value_kind:     hidden_global_offset_z
      - .offset:         280
        .size:           2
        .value_kind:     hidden_grid_dims
      - .offset:         304
        .size:           8
        .value_kind:     hidden_multigrid_sync_arg
      - .offset:         336
        .size:           4
        .value_kind:     hidden_dynamic_lds_size
    .group_segment_fixed_size: 0
    .kernarg_segment_align: 8
    .kernarg_segment_size: 472
    .language:       OpenCL C
    .language_version:
      - 2
      - 0
    .max_flat_workgroup_size: 512
    .name:           _Z14fwd_megakernel3Prm
    .private_segment_fixed_size: 0
    .sgpr_count:     108
    .sgpr_spill_count: 60
    .symbol:         _Z14fwd_megakernel3Prm.kd
    .uniform_work_group_size: 1
    .uses_dynamic_stack: false
    .vgpr_count:     256
    .vgpr_spill_count: 0
    .wavefront_size: 64
